# final phase rows remapped group-local (G==256) so the last seam also uses the XCD-group barrier; on top of v76
# baseline (speedup 1.0000x reference)
; __device__ __forceinline__ unsigned xb_ld(unsigned* p)              { return __hip_atomic_load(p, __ATOMIC_RELAXED, __HIP_MEMORY_SCOPE_AGENT); }
; __device__ __forceinline__ unsigned xb_add(unsigned* p, unsigned v) { return __hip_atomic_fetch_add(p, v, __ATOMIC_RELAXED, __HIP_MEMORY_SCOPE_AGENT); }
; #define XB_SPIN(cond, bar) do { unsigned _sp = 0; while (cond) { __builtin_amdgcn_s_sleep(1); \
;     if ((++_sp & 255u) == 0u) { if (xb_ld(&(bar)[XB_TMO])) break; if (_sp > XB_SPIN_CAP) { atomicAdd(&(bar)[XB_TMO], 1u); break; } } } } while (0)
; #define PH_BEGIN if (pid >= lo && pid < hi) {
; #define PH_END   if (pid + 1 < hi) xcd_barrier(bar); } ++pid;
; __device__ __forceinline__ void xcd_barrier(const XcdBarrier& b) {
;     asm volatile("s_waitcnt vmcnt(0)" ::: "memory");
;     __syncthreads();
;     if (threadIdx.x == 0) {
;         unsigned* bar = b.bar;
;         __builtin_amdgcn_s_waitcnt(0);
;         unsigned nloc = b.st[0], nx = b.st[1];
;         if (nloc == 0u) { xcd_barrier_complete(bar, b.x, nloc, nx); b.st[0] = nloc; b.st[1] = nx; }
;         const unsigned old = xb_add(&bar[XB_XSUB(b.x)], 1u);
;         const unsigned gen = old / nloc;
;         if (old + 1u == (gen + 1u) * nloc) {
;             __builtin_amdgcn_fence(__ATOMIC_RELEASE, "agent");
;             asm volatile("s_waitcnt vmcnt(0)" ::: "memory");
;             const unsigned og = xb_add(&bar[XB_TOP], 1u);
;             const unsigned tg = og / nx;
;             if (og + 1u == (tg + 1u) * nx) xb_add(&bar[XB_TOPGEN], 1u);
;             else XB_SPIN(xb_ld(&bar[XB_TOPGEN]) == tg, bar);
;             __builtin_amdgcn_fence(__ATOMIC_ACQUIRE, "agent");
;             xb_add(&bar[XB_XGEN(b.x)], 1u);
;             asm volatile("s_waitcnt vmcnt(0)" ::: "memory");
;         } else {
;             XB_SPIN(xb_ld(&bar[XB_XGEN(b.x)]) == gen, bar);
;             __builtin_amdgcn_fence(__ATOMIC_ACQUIRE, "agent");
;             asm volatile("s_waitcnt vmcnt(0)" ::: "memory");
;         }
;     }
;     __syncthreads();
; }
; __global__ void __launch_bounds__(NTHREADS, 2) fwd_kernel(Args a) {
;     ...
;             pg8::gemm_phase<pg8::EpiRes, pg8::StaticOrder, true, true>(lds, g, S, E);
;             PH_END
;         }
;     }
;     PH_BEGIN final_phase(XB, a.out, ssqA, a.in[3], G, wg); PH_END
.LBB0_1868:
	s_add_i32 s0, s66, 3
	s_mov_b32 s86, s0
	s_cmp_ge_i32 s0, s27
	s_cbranch_scc1 .LBB0_1922
	s_waitcnt vmcnt(0)
	s_waitcnt vmcnt(0) lgkmcnt(0)
	s_barrier
	s_mov_b64 s[0:1], exec
	v_readlane_b32 s8, v252, 32
	v_readlane_b32 s9, v252, 33
	s_and_b64 s[8:9], s[0:1], s[8:9]
	s_mov_b64 exec, s[8:9]
	s_cbranch_execz .LBB0_1921
	v_mov_b32_e32 v0, 0x23fc8
	ds_read_b32 v1, v0
	s_waitcnt lgkmcnt(0)
	v_readfirstlane_b32 s40, v1
	s_cmp_eq_u32 s40, 1
	s_cbranch_scc0 .Lgb_orig_g4
	s_and_b32 s40, s2, 7
	s_lshl_b32 s40, s40, 7
	s_add_u32 s38, s24, 0x313800
	s_addc_u32 s39, s25, 0
	v_mov_b32_e32 v0, s40
	v_mov_b32_e32 v1, 1
	global_atomic_add v2, v0, v1, s[38:39] sc0
	s_mov_b32 s40, 0
	s_waitcnt vmcnt(0)
	buffer_inv sc1
	v_or_b32_e32 v2, 31, v2
	v_add_u32_e32 v2, 1, v2

; __device__ __forceinline__ int opaque_tid() { int t = threadIdx.x; asm volatile("" : "+v"(t)); return t; }
; __device__ __forceinline__ void final_phase(const bf16_t* xb, float* out, const float* ssq, const float* gain, int G, int wg) {
;     const int tid = opaque_tid(), lane = tid & 63, wave = tid >> 6; const int gw = wg * 8 + wave, NGW = G * 8;
;     f32x4 gv[4];
; #pragma unroll
;     for (int j = 0; j < 4; ++j) gv[j] = ((const f32x4*)gain)[lane + 64 * j];
;     for (int m = gw; m < MT; m += NGW) {
;         const float rs = __builtin_amdgcn_rsqf(pg8::ssq_row(ssq, m) * (1.f / 1024.f) + EPS);
;         const u32x2* xr = (const u32x2*)(xb + (size_t)m * DM) + lane; f32x4* orow = (f32x4*)(out + (size_t)m * DM) + lane;
.LBB0_1924:
	s_cmp_ge_i32 s86, s26
	s_cselect_b64 s[0:1], -1, 0
	s_cmp_lt_i32 s86, s27
	s_cselect_b64 s[2:3], -1, 0
	s_and_b64 s[0:1], s[0:1], s[2:3]
	s_and_b64 vcc, exec, s[0:1]
	s_cbranch_vccz .LBB0_1982
	v_readlane_b32 s4, v254, 52
	s_movk_i32 s8, 0x7fff
	s_cmp_eq_u32 s28, 0x100
	s_cbranch_scc0 .Lfr_keep
	s_lshr_b32 s0, s4, 3
	s_and_b32 s4, s0, 7
	s_lshl_b32 s4, s4, 12
	s_or_b32 s8, s4, 0xfff
	s_lshr_b32 s0, s0, 3
	s_lshl_b32 s0, s0, 3
	s_add_i32 s4, s4, s0
.Lfr_keep:
	v_ashrrev_i32_e32 v16, 6, v210
	s_mov_b32 s0, 0x8000
	v_add_u32_e32 v22, s4, v16
	v_cmp_gt_i32_e32 vcc, s0, v22
	v_readlane_b32 s5, v254, 53
	s_and_saveexec_b64 s[0:1], vcc
	v_readlane_b32 s12, v253, 53
	s_cmp_eq_u32 s28, 0x100
	s_cselect_b32 s12, 0x100, s12
	v_readlane_b32 s13, v253, 54
	s_cbranch_execz .LBB0_1928
	v_and_b32_e32 v23, 63, v210
	s_waitcnt vmcnt(0)
	v_lshlrev_b32_e32 v24, 4, v23
	s_waitcnt lgkmcnt(0)
	global_load_dwordx4 v[0:3], v24, s[74:75]
	global_load_dwordx4 v[4:7], v24, s[74:75] offset:1024
	global_load_dwordx4 v[8:11], v24, s[74:75] offset:2048
	global_load_dwordx4 v[12:15], v24, s[74:75] offset:3072
	v_ashrrev_i32_e32 v17, 31, v16
	s_ashr_i32 s5, s4, 31
	v_lshl_add_u64 v[20:21], v[16:17], 0, s[4:5]
	v_lshlrev_b64 v[16:17], 6, v[20:21]
	v_lshlrev_b64 v[18:19], 12, v[20:21]
	v_readlane_b32 s36, v252, 16
	v_lshlrev_b64 v[20:21], 11, v[20:21]
	v_or_b32_e32 v18, v18, v24
	v_readlane_b32 s46, v252, 26
	v_readlane_b32 s47, v252, 27
	v_readlane_b32 s50, v252, 30
	v_readlane_b32 s51, v252, 31
	v_lshl_or_b32 v20, v23, 3, v20
	v_lshl_add_u64 v[16:17], s[24:25], 0, v[16:17]
	s_ashr_i32 s13, s12, 31
	v_readlane_b32 s46, v252, 46
	v_lshl_add_u64 v[18:19], s[50:51], 0, v[18:19]
	s_mov_b64 s[4:5], 0x800
	v_lshl_add_u64 v[20:21], s[24:25], 0, v[20:21]
	s_mov_b64 s[6:7], 0x6200400
	v_lshl_add_u64 v[16:17], v[16:17], 0, 32
	s_lshl_b64 s[2:3], s[12:13], 6
	v_readlane_b32 s47, v252, 47
	v_lshl_add_u64 v[18:19], v[18:19], 0, s[4:5]
	s_lshl_b64 s[4:5], s[12:13], 12
	v_lshl_add_u64 v[20:21], v[20:21], 0, s[6:7]
	s_lshl_b64 s[6:7], s[12:13], 11
	s_mov_b64 s[10:11], 0
	v_mov_b32_e32 v23, 0x358637bd
	v_readlane_b32 s37, v252, 17
	v_readlane_b32 s38, v252, 18
	v_readlane_b32 s39, v252, 19
	v_readlane_b32 s40, v252, 20
	v_readlane_b32 s41, v252, 21
	v_readlane_b32 s42, v252, 22
	v_readlane_b32 s43, v252, 23
	v_readlane_b32 s44, v252, 24
	v_readlane_b32 s45, v252, 25
	v_readlane_b32 s48, v252, 28
	v_readlane_b32 s49, v252, 29
